# v015 plus SWA unit head: sink load hoisted before next-window prefetch, counted vmcnt so prefetch stays in flight during the unit
# baseline (speedup 1.0000x reference)
; #define LAS __attribute__((address_space(3)))
; __device__ __forceinline__ void swa_phase_wg(const bf16_t* qkv, const float* sinks, bf16_t* att, LAS unsigned char* lds, int bid, int G, int tid, int wave, int lane) {
;     ...
;     for (; u < NU; u += G) {
;         const int un = u + G; const bool has_next = un < NU;
;         const int blk = u % NBLK, kvh = (u / NBLK) & 3, b = u / (4 * NBLK);
;         const int t0 = 32 * blk, tq = t0 + 4 * wave + qi; const size_t rb = (size_t)b * T;
;         bf16x8 qr[4];
;         const bf16_t* qp = qkv + (rb + tq) * LDQ + QOFF + (kvh * 8 + g) * 64 + 8 * hi;
; #pragma unroll
;         for (int ks = 0; ks < 4; ++ks) qr[ks] = *(const bf16x8*)(qp + 16 * ks);
;         if (has_next) SW_LOAD(un);
;         const LAS unsigned char* buf = lds + pb * BUF;
;         const float sk = sinks[kvh * 8 + g] * LOG2E;
;         f32x16 o0 = {}, o1 = {}; float m = sk, l = 0.f;
;         const unsigned lim = (unsigned)min(127, tq);
;         int dbase = 128 + 4 * wave + qi - 4 * hi;
.LBB0_534:
	s_ashr_i32 s0, s25, 31
	s_lshr_b32 s1, s0, 24
	s_add_i32 s8, s25, s1
	s_lshr_b32 s0, s0, 22
	s_and_b32 s1, s8, 0x7ffff00
	s_add_i32 s0, s25, s0
	s_sub_i32 s1, s25, s1
	s_ashr_i32 s0, s0, 10
	v_lshl_add_u32 v2, s1, 5, v133
	s_ashr_i32 s1, s0, 31
	s_lshl_b64 s[0:1], s[0:1], 13
	v_ashrrev_i32_e32 v3, 31, v2
	v_lshl_add_u64 v[124:125], s[0:1], 0, v[2:3]
	v_mov_b64_e32 v[4:5], s[36:37]
	v_mad_u64_u32 v[4:5], s[0:1], v124, s56, v[4:5]
	s_lshr_b32 s0, s8, 5
	s_nop 0
	v_and_or_b32 v3, s0, 24, v130
	v_mad_i32_i24 v5, v125, s56, v5
	v_lshlrev_b32_e32 v0, 7, v3
	v_lshl_add_u64 v[4:5], v[4:5], 0, v[0:1]
	v_lshl_add_u64 v[4:5], v[120:121], 1, v[4:5]
	global_load_dwordx4 v[112:115], v[4:5], off
	global_load_dwordx4 v[108:111], v[4:5], off offset:32
	global_load_dwordx4 v[104:107], v[4:5], off offset:64
	global_load_dwordx4 v[100:103], v[4:5], off offset:96
	v_lshlrev_b32_e32 v251, 2, v3
	global_load_dword v251, v251, s[4:5]
	s_add_i32 s25, s25, s26
	s_cmpk_lt_i32 s25, 0x800
	s_cselect_b64 s[10:11], -1, 0
	s_cmpk_gt_i32 s25, 0x7ff
	s_cselect_b64 s[8:9], -1, 0
	s_and_b64 vcc, exec, s[8:9]
	s_cbranch_vccnz .Lswa_nopf
	s_ashr_i32 s0, s25, 31
	s_lshr_b32 s1, s0, 24
	s_add_i32 s1, s25, s1
	s_and_b32 s14, s1, 0x7ffff00
	s_lshr_b32 s0, s0, 22
	s_sub_i32 s14, s25, s14
	s_add_i32 s0, s25, s0
	s_ashr_i32 s0, s0, 10
	s_lshl_b32 s14, s14, 5
	s_addk_i32 s14, 0xff80
	s_mul_hi_i32 s15, s0, 0x3c00000
	s_mul_i32 s0, s0, 0x3c00000
	s_add_u32 s0, s36, s0
	s_addc_u32 s15, s37, s15
	s_lshr_b32 s1, s1, 1
	s_and_b32 s1, s1, 0x180
	s_add_u32 s0, s0, s1
	v_add_u32_e32 v0, s14, v117
	s_addc_u32 s1, s15, 0
	v_mov_b32_e32 v123, v1
	v_med3_i32 v0, v0, 0, v228
	v_lshl_add_u64 v[4:5], s[0:1], 0, v[122:123]
	v_mul_u32_u24_e32 v0, 0x1e00, v0
	v_lshl_add_u64 v[6:7], v[4:5], 0, v[0:1]
	v_add_u32_e32 v0, s14, v126
	v_med3_i32 v0, v0, 0, v228
	v_mul_u32_u24_e32 v0, 0x1e00, v0
	v_lshl_add_u64 v[8:9], v[4:5], 0, v[0:1]
	v_add_u32_e32 v0, s14, v127
	v_med3_i32 v0, v0, 0, v228
	v_mul_u32_u24_e32 v0, 0x1e00, v0
	global_load_dwordx4 v[80:83], v[6:7], off
	global_load_dwordx4 v[84:87], v[8:9], off
	v_lshl_add_u64 v[6:7], v[4:5], 0, v[0:1]
	v_add_u32_e32 v0, s14, v128
	v_med3_i32 v0, v0, 0, v228
	v_mul_u32_u24_e32 v0, 0x1e00, v0
	v_lshl_add_u64 v[8:9], v[4:5], 0, v[0:1]
	v_add_u32_e32 v0, s14, v129
	v_med3_i32 v0, v0, 0, v228
	v_mul_u32_u24_e32 v0, 0x1e00, v0
	v_lshl_add_u64 v[4:5], v[4:5], 0, v[0:1]
	global_load_dwordx4 v[88:91], v[6:7], off
	global_load_dwordx4 v[92:95], v[8:9], off
	global_load_dwordx4 v[96:99], v[4:5], off
	s_waitcnt vmcnt(5)
.LBB0_536:
	s_mul_i32 s0, s24, 0xa000
	v_mov_b32_e32 v14, v1
	v_mov_b32_e32 v15, v1
	v_lshlrev_b32_e32 v123, 6, v3
	s_add_i32 s0, s0, 0
	v_min_i32_e32 v155, 0x7f, v2
	v_mov_b32_e32 v2, v1
	v_mov_b32_e32 v3, v1
	v_mov_b32_e32 v4, v1
	v_mov_b32_e32 v5, v1
	v_mov_b32_e32 v6, v1
	v_mov_b32_e32 v7, v1
	v_mov_b32_e32 v8, v1
	v_mov_b32_e32 v9, v1
	v_mov_b32_e32 v10, v1
	v_mov_b32_e32 v11, v1
	v_mov_b32_e32 v12, v1
	v_mov_b32_e32 v13, v1
	v_add_u32_e32 v156, s0, v134
	v_add_u32_e32 v153, s0, v131
	s_mov_b32 s27, 0
	v_mov_b32_e32 v154, 0
	s_mov_b64 s[0:1], -1
	v_mov_b32_e32 v158, v151
	v_mov_b32_e32 v157, v150
	v_mul_f32_e32 v152, 0x3fb8aa3b, v251
	v_mov_b32_e32 v0, v1
	v_mov_b64_e32 v[30:31], v[14:15]
	v_mov_b64_e32 v[46:47], v[14:15]
	v_mov_b64_e32 v[28:29], v[12:13]
	v_mov_b64_e32 v[26:27], v[10:11]
	v_mov_b64_e32 v[24:25], v[8:9]
	v_mov_b64_e32 v[22:23], v[6:7]
	v_mov_b64_e32 v[20:21], v[4:5]
	v_mov_b64_e32 v[18:19], v[2:3]
	v_mov_b64_e32 v[16:17], v[0:1]
	v_mov_b64_e32 v[44:45], v[12:13]
	v_mov_b64_e32 v[42:43], v[10:11]
	v_mov_b64_e32 v[40:41], v[8:9]
	v_mov_b64_e32 v[38:39], v[6:7]
	v_mov_b64_e32 v[36:37], v[4:5]
	v_mov_b64_e32 v[34:35], v[2:3]
	v_mov_b64_e32 v[32:33], v[0:1]
	v_mov_b32_e32 v0, v152
	s_branch .LBB0_538

; __device__ __forceinline__ unsigned cvt_pk_bf16(float lo, float hi) { unsigned r; asm volatile("v_cvt_pk_bf16_f32 %0, %1, %2" : "=v"(r) : "v"(lo), "v"(hi)); return r; }
; __device__ __forceinline__ float ex2(float x) { return __builtin_amdgcn_exp2f(x); }
; __device__ __forceinline__ s16x4 vtr(const LAS unsigned char* p) { return __builtin_bit_cast(s16x4, __builtin_amdgcn_ds_read_tr16_b64_v4i16((LAS v4i16_t*)p)); }
; template <bool HALF> ...
;     ...
;     for (int gq = 0; gq < ((HALF || half_rt) ? 2 : 4); ++gq) {
;         float e[8];
; #pragma unroll
;         for (int i = 0; i < 8; ++i) { const float x = (gq < 2) ? p0[8 * (gq & 1) + i] : p1[8 * (gq & 1) + i]; e[i] = ex2(x - mu); ls += e[i]; }
;         u32x4 w; w.x = pg8::cvt_pk_bf16(e[0], e[1]); w.y = pg8::cvt_pk_bf16(e[2], e[3]); w.z = pg8::cvt_pk_bf16(e[4], e[5]); w.w = pg8::cvt_pk_bf16(e[6], e[7]);
;         pa[gq] = __builtin_bit_cast(bf16x8, w);
;     }
;     l += ls;
;     __builtin_amdgcn_s_setprio(1);
; #pragma unroll
;     for (int kk = 0; kk < ((HALF || half_rt) ? 2 : 4); ++kk) {
;         const s16x4 lo0 = vtr(Vt + vb + kk * 1024), hi0 = vtr(Vt + vb + kk * 1024 + 512);
;         const s16x4 lo1 = vtr(Vt + vb + vplane + kk * 1024), hi1 = vtr(Vt + vb + vplane + kk * 1024 + 512);
;         const bf16x8 v0 = (bf16x8){lo0[0], lo0[1], lo0[2], lo0[3], hi0[0], hi0[1], hi0[2], hi0[3]};
;         const bf16x8 v1 = (bf16x8){lo1[0], lo1[1], lo1[2], lo1[3], hi1[0], hi1[1], hi1[2], hi1[3]};
;         o0 = __builtin_amdgcn_mfma_f32_32x32x16_bf16(v0, pa[kk], o0, 0, 0, 0);
;         o1 = __builtin_amdgcn_mfma_f32_32x32x16_bf16(v1, pa[kk], o1, 0, 0, 0);
;     }
; __device__ __forceinline__ void swa_phase_wg(const bf16_t* qkv, const float* sinks, bf16_t* att, LAS unsigned char* lds, int bid, int G, int tid, int wave, int lane) {
;     ...
;         l += __shfl_xor(l, 32); l += ex2(sk - m);
;         attn_store(att + (rb + tq) * D + (kvh * 8 + g) * 64, o0, o1, 1.0f / l, hi);
;         asm volatile("" ::: "memory");
;         if (has_next) SW_STORE(lds + (pb ^ 1) * BUF);
.LBB0_546:
	v_sub_f32_e32 v50, v64, v2
	v_exp_f32_e32 v50, v50
	v_sub_f32_e32 v49, v49, v2
	v_exp_f32_e32 v49, v49
	v_sub_f32_e32 v48, v48, v2
	v_exp_f32_e32 v48, v48
	v_sub_f32_e32 v15, v15, v2
	v_exp_f32_e32 v15, v15
	v_sub_f32_e32 v14, v14, v2
	v_add_f32_e32 v51, 0, v50
	v_exp_f32_e32 v14, v14
	v_sub_f32_e32 v13, v13, v2
	v_add_f32_e32 v51, v49, v51
	v_exp_f32_e32 v52, v13
	v_sub_f32_e32 v12, v12, v2
	v_add_f32_e32 v51, v48, v51
	v_exp_f32_e32 v53, v12
	v_sub_f32_e32 v11, v11, v2
	v_add_f32_e32 v51, v15, v51
	v_exp_f32_e32 v11, v11
	v_sub_f32_e32 v10, v10, v2
	v_add_f32_e32 v12, v14, v51
	v_exp_f32_e32 v10, v10
	v_sub_f32_e32 v9, v9, v2
	v_add_f32_e32 v12, v52, v12
	v_exp_f32_e32 v9, v9
	v_sub_f32_e32 v8, v8, v2
	v_add_f32_e32 v12, v53, v12
	v_exp_f32_e32 v8, v8
	v_sub_f32_e32 v7, v7, v2
	v_add_f32_e32 v51, v11, v12
	v_exp_f32_e32 v7, v7
	v_sub_f32_e32 v6, v6, v2
	v_cvt_pk_bf16_f32 v12, v50, v49
	v_cvt_pk_bf16_f32 v13, v48, v15
	v_cvt_pk_bf16_f32 v14, v14, v52
	v_cvt_pk_bf16_f32 v15, v53, v11
	v_add_f32_e32 v11, v10, v51
	v_exp_f32_e32 v6, v6
	v_sub_f32_e32 v5, v5, v2
	v_add_f32_e32 v11, v9, v11
	v_exp_f32_e32 v5, v5
	v_sub_f32_e32 v4, v4, v2
	v_add_f32_e32 v11, v8, v11
	v_exp_f32_e32 v48, v4
	v_sub_f32_e32 v2, v3, v2
	v_add_f32_e32 v11, v7, v11
	v_exp_f32_e32 v49, v2
	v_add_f32_e32 v2, v6, v11
	v_add_f32_e32 v2, v5, v2
	v_add_f32_e32 v2, v48, v2
	v_add_f32_e32 v11, v49, v2
	v_cvt_pk_bf16_f32 v2, v10, v9
	v_cvt_pk_bf16_f32 v3, v8, v7
	v_cvt_pk_bf16_f32 v4, v6, v5
	v_cvt_pk_bf16_f32 v5, v48, v49
	v_add_f32_e32 v52, v154, v11
	s_setprio 1
	ds_read_b64_tr_b16 v[6:7], v153 offset:28672
	ds_read_b64_tr_b16 v[8:9], v153 offset:29184
	ds_read_b64_tr_b16 v[48:49], v153 offset:38912
	ds_read_b64_tr_b16 v[50:51], v153 offset:39424
	s_waitcnt lgkmcnt(2)
	v_mfma_f32_32x32x16_bf16 v[16:31], v[6:9], v[12:15], v[16:31]
	ds_read_b64_tr_b16 v[6:7], v153 offset:29696
	ds_read_b64_tr_b16 v[8:9], v153 offset:30208
	ds_read_b64_tr_b16 v[10:11], v153 offset:39936
	s_waitcnt lgkmcnt(3)
	v_mfma_f32_32x32x16_bf16 v[32:47], v[48:51], v[12:15], v[32:47]
	ds_read_b64_tr_b16 v[12:13], v153 offset:40448
	s_waitcnt lgkmcnt(2)
	v_mfma_f32_32x32x16_bf16 v[16:31], v[6:9], v[2:5], v[16:31]
	s_waitcnt lgkmcnt(0)
	v_mfma_f32_32x32x16_bf16 v[32:47], v[10:13], v[2:5], v[32:47]
	s_setprio 0
	v_and_b32_e32 v3, 64, v226
	v_xor_b32_e32 v2, 32, v226
	v_add_u32_e32 v3, 64, v3
	v_cmp_lt_i32_e32 vcc, v2, v3
	v_sub_f32_e32 v0, v152, v0
	v_exp_f32_e32 v0, v0
	v_cndmask_b32_e32 v2, v226, v2, vcc
	v_lshlrev_b32_e32 v2, 2, v2
	ds_bpermute_b32 v2, v2, v52
	s_xor_b32 s24, s24, 1
	s_waitcnt lgkmcnt(0)
	v_add_f32_e32 v2, v52, v2
	v_add_f32_e32 v4, v0, v2
	v_div_scale_f32 v5, s[0:1], v4, v4, 1.0
	v_rcp_f32_e32 v6, v5
	v_readlane_b32 s0, v250, 11
	v_lshlrev_b64 v[2:3], 12, v[124:125]
	v_readlane_b32 s1, v250, 12
	v_lshlrev_b32_e32 v0, 1, v123
	s_nop 0
	v_lshl_add_u64 v[2:3], s[0:1], 0, v[2:3]
	v_lshl_add_u64 v[2:3], v[2:3], 0, v[0:1]
	v_fma_f32 v0, -v5, v6, 1.0
	v_fmac_f32_e32 v6, v0, v6
	v_div_scale_f32 v0, vcc, 1.0, v4, 1.0
	v_mul_f32_e32 v7, v0, v6
	v_fma_f32 v8, -v5, v7, v0
	v_fmac_f32_e32 v7, v8, v6
	v_fma_f32 v0, -v5, v7, v0
	v_div_fmas_f32 v0, v0, v6, v7
	v_div_fixup_f32 v0, v0, v4, 1.0
	v_mul_f32_e32 v4, v16, v0
	v_mul_f32_e32 v5, v17, v0
	v_cvt_pk_bf16_f32 v4, v4, v5
	v_mul_f32_e32 v5, v18, v0
	v_mul_f32_e32 v6, v19, v0
	v_cvt_pk_bf16_f32 v5, v5, v6
	v_mul_f32_e32 v6, v32, v0
	v_mul_f32_e32 v7, v33, v0
	v_lshl_add_u64 v[2:3], v[118:119], 1, v[2:3]
	v_cvt_pk_bf16_f32 v6, v6, v7
	v_mul_f32_e32 v7, v34, v0
	v_mul_f32_e32 v8, v35, v0
	v_cvt_pk_bf16_f32 v7, v7, v8
	global_store_dwordx2 v[2:3], v[4:5], off
	global_store_dwordx2 v[2:3], v[6:7], off offset:64
	v_mul_f32_e32 v4, v20, v0
	v_mul_f32_e32 v5, v21, v0
	v_cvt_pk_bf16_f32 v4, v4, v5
	v_mul_f32_e32 v5, v22, v0
	v_mul_f32_e32 v6, v23, v0
	v_cvt_pk_bf16_f32 v5, v5, v6
	v_mul_f32_e32 v6, v36, v0
	v_mul_f32_e32 v7, v37, v0
	v_cvt_pk_bf16_f32 v6, v6, v7
	v_mul_f32_e32 v7, v38, v0
	v_mul_f32_e32 v8, v39, v0
	v_cvt_pk_bf16_f32 v7, v7, v8
	global_store_dwordx2 v[2:3], v[4:5], off offset:16
	global_store_dwordx2 v[2:3], v[6:7], off offset:80
	v_mul_f32_e32 v4, v24, v0
	v_mul_f32_e32 v5, v25, v0
	v_cvt_pk_bf16_f32 v4, v4, v5
	v_mul_f32_e32 v5, v26, v0
	v_mul_f32_e32 v6, v27, v0
	v_cvt_pk_bf16_f32 v5, v5, v6
	v_mul_f32_e32 v6, v40, v0
	v_mul_f32_e32 v7, v41, v0
	v_cvt_pk_bf16_f32 v6, v6, v7
	v_mul_f32_e32 v7, v42, v0
	v_mul_f32_e32 v8, v43, v0
	v_cvt_pk_bf16_f32 v7, v7, v8
	global_store_dwordx2 v[2:3], v[4:5], off offset:32
	global_store_dwordx2 v[2:3], v[6:7], off offset:96
	v_mul_f32_e32 v4, v28, v0
	v_mul_f32_e32 v5, v29, v0
	v_cvt_pk_bf16_f32 v4, v4, v5
	v_mul_f32_e32 v5, v30, v0
	v_mul_f32_e32 v6, v31, v0
	v_cvt_pk_bf16_f32 v5, v5, v6
	v_mul_f32_e32 v6, v44, v0
	v_mul_f32_e32 v7, v45, v0
	v_cvt_pk_bf16_f32 v6, v6, v7
	v_mul_f32_e32 v7, v46, v0
	v_mul_f32_e32 v0, v47, v0
	v_cvt_pk_bf16_f32 v7, v7, v0
	global_store_dwordx2 v[2:3], v[4:5], off offset:48
	global_store_dwordx2 v[2:3], v[6:7], off offset:112
	s_andn2_b64 vcc, exec, s[10:11]
	s_cbranch_vccnz .LBB0_533
	s_waitcnt vmcnt(8)
	s_mul_i32 s10, s24, 0xa000
	v_add_u32_e32 v0, s10, v149
	s_and_saveexec_b64 s[0:1], s[6:7]
	s_xor_b64 s[0:1], exec, s[0:1]
	s_cbranch_execnz .LBB0_557
	s_or_saveexec_b64 s[0:1], s[0:1]
	v_add_u32_e32 v2, s10, v132
	s_xor_b64 exec, exec, s[0:1]
	s_cbranch_execnz .LBB0_558

; #define LAS __attribute__((address_space(3)))
; #define SW_STORE(buf_) do { _Pragma("unroll") for (int i_ = 0; i_ < 5; ++i_) { const int id_ = tid + 512 * i_, row_ = id_ >> 4, c_ = id_ & 15; \
;       if (c_ < 8) *(LAS u32x4*)((buf_) + row_ * 128 + ((c_ ^ ((row_ >> 1) & 7)) * 16)) = st[i_]; \
;       else *(LAS u32x4*)((buf_) + KIMG + ((c_ - 8) >> 2) * VPL + row_ * 64 + ((c_ - 8) & 3) * 16) = st[i_]; } } while (0)
; #define DF_LOAD(Kg_, t_) do { _Pragma("unroll") for (int i_ = 0; i_ < 8; ++i_) { const int p_ = idx[64 * (t_) + 8 * i_ + srow_]; \
;       const bf16_t* rp_ = (Kg_) + (size_t)p_ * LDQ + sc_ * 8; kreg[i_] = *(const u32x4*)rp_; vreg[i_] = *(const u32x4*)(rp_ + (VOFF - KOFF)); } } while (0)
; __device__ __forceinline__ void swa_phase_wg(const bf16_t* qkv, const float* sinks, bf16_t* att, LAS unsigned char* lds, int bid, int G, int tid, int wave, int lane) {
;     ...
;         if (has_next) SW_STORE(lds + (pb ^ 1) * BUF);
;         __syncthreads();
;         pb ^= 1;
; __device__ __forceinline__ void dsa_fused_phase(const bf16_t* qkv, const float* scores, bf16_t* att, LAS unsigned char* wl, int gw, int NGW, int lane) {
;     const int c16 = lane & 15, qp = lane >> 4, hi = lane >> 5, g = c16 & 7;
;     LAS unsigned char* Kl = wl; LAS unsigned char* Vl = wl + 8192; LAS int* idx = (LAS int*)(wl + 16384);
;     const int srow_ = lane >> 3, sc_ = lane & 7;
;     const int vb16 = (4 * qp + ((lane & 15) >> 2)) * 64 + (lane & 3) * 8;
;     for (int u = gw; u < M; u += NGW) {
;         const int b = u / T, tt = u % T, t = ((tt >> 11) & 1) ? ((tt & ~2047) + 2047 - (tt & 2047)) : tt;
;         const size_t rb = (size_t)b * T; const int n = t + 1, count = min(256, n), ntiles = (count + 63) >> 6;
;         const float* srow = scores + score_off(b, t);
;         if (n <= 256) { for (int i = lane; i < 256; i += 64) idx[i] = (i < n) ? i : 0; }
;         else select256(wl, srow, n, lane);
;         asm volatile("" ::: "memory");
;         const bf16_t* Kg0 = qkv + rb * LDQ + KOFF;
;         bf16x8 q16[2];
;         { const bf16_t* qp_ = qkv + (rb + t) * LDQ + QOFF + g * 64 + 8 * qp;
; #pragma unroll
;           for (int ks = 0; ks < 2; ++ks) q16[ks] = *(const bf16x8*)(qp_ + 32 * ks); }
;         u32x4 kreg[8], vreg[8];
;     ...
;         DF_LOAD(Kg0, 0); DF_STORE();
.LBB0_566:
	v_add_u32_e32 v0, v2, v148
	ds_write_b128 v0, v[96:99]
	s_branch .LBB0_532
.Lswa_nopf:
	s_waitcnt vmcnt(0)
	s_branch .LBB0_536
.LBB0_567:
	s_and_b64 vcc, exec, s[40:41]
	s_cbranch_vccnz .LBB0_1311
	v_readlane_b32 s0, v249, 40
	v_readlane_b32 s1, v249, 41
	s_andn2_b64 vcc, exec, s[0:1]
	s_cbranch_vccnz .LBB0_1311
	v_lshlrev_b32_e32 v10, 10, v116
	v_lshlrev_b32_e32 v11, 4, v116
	v_and_b32_e32 v10, 0x1000, v10
	v_and_b32_e32 v12, 48, v11
	s_waitcnt vmcnt(0)
	v_ashrrev_i32_e32 v6, 4, v116
	v_cmp_gt_i32_e64 s[0:1], s29, v116
	v_add3_u32 v10, s33, v10, v12
	v_bfe_u32 v12, v116, 1, 3
	v_lshlrev_b32_e32 v106, 2, v6
	v_writelane_b32 v248, s0, 30
	v_lshlrev_b32_e32 v4, 3, v6
	v_xor_b32_e32 v13, v12, v6
	v_add_u32_e32 v6, 4, v6
	v_writelane_b32 v248, s1, 31
	v_cmp_gt_i32_e64 s[0:1], 63, v116
	v_xor_b32_e32 v6, v6, v12
	v_ashrrev_i32_e32 v7, 3, v116
	v_writelane_b32 v248, s0, 32
	v_lshlrev_b32_e32 v140, 4, v6
	v_and_b32_e32 v6, 16, v116
	v_writelane_b32 v248, s1, 33
	v_cmp_gt_i32_e64 s[0:1], 62, v116
	v_cmp_eq_u32_e64 s[60:61], 0, v6
	v_lshrrev_b32_e32 v6, 1, v7
	v_writelane_b32 v248, s0, 34
	v_xor_b32_e32 v6, v6, v116
	v_lshlrev_b32_e32 v6, 4, v6
	v_writelane_b32 v248, s1, 35
	v_cmp_gt_i32_e64 s[0:1], 64, v116
	v_lshlrev_b32_e32 v139, 4, v13
	v_and_b32_e32 v13, 0x70, v6
	v_writelane_b32 v248, s0, 36
	v_add_u32_e32 v6, 8, v7
	v_lshl_add_u32 v15, v6, 7, s33
	v_writelane_b32 v248, s1, 37
	v_cmp_gt_i32_e64 s[0:1], s54, v116
	v_lshrrev_b32_e32 v16, 1, v6
	v_lshlrev_b32_e32 v17, 6, v6
	v_add_u32_e32 v6, 16, v7
	v_writelane_b32 v248, s0, 38
	v_lshl_add_u32 v18, v6, 7, s33
	v_lshlrev_b32_e32 v19, 6, v6
	v_add_u32_e32 v6, 24, v7
	v_bfe_u32 v2, v116, 2, 2
	v_lshlrev_b32_e32 v3, 3, v116
	v_writelane_b32 v248, s1, 39
	v_cmp_gt_i32_e64 s[0:1], 16, v116
	v_lshl_add_u32 v20, v6, 7, s33
	v_lshrrev_b32_e32 v21, 1, v6
	v_lshlrev_b32_e32 v22, 6, v6
	v_add_u32_e32 v6, 32, v7
	v_or_b32_e32 v2, v106, v2
	v_and_b32_e32 v3, 24, v3
	v_writelane_b32 v248, s0, 40
	v_lshl_add_u32 v23, v6, 7, s33
	v_lshlrev_b32_e32 v24, 6, v6
	v_add_u32_e32 v6, 40, v7
	v_lshl_or_b32 v132, v2, 6, v3
	v_lshlrev_b64 v[2:3], v116, -1
	v_writelane_b32 v248, s1, 41
	v_readlane_b32 s0, v250, 11
	v_lshl_add_u32 v25, v6, 7, s33
	v_lshrrev_b32_e32 v26, 1, v6
	v_lshlrev_b32_e32 v27, 6, v6
	v_add_u32_e32 v6, 48, v7
	v_not_b32_e32 v109, v3
	v_and_b32_e32 v3, 63, v116
	v_ashrrev_i32_e32 v107, 31, v106
	v_readlane_b32 s1, v250, 12
	v_lshl_add_u32 v28, v6, 7, s33
	v_lshlrev_b32_e32 v29, 6, v6
	v_add_u32_e32 v6, 56, v7
	v_lshlrev_b32_e32 v9, 2, v7
	v_lshl_add_u64 v[112:113], v[106:107], 1, s[0:1]
	v_lshl_add_u32 v12, v7, 7, s33
	v_lshlrev_b32_e32 v14, 6, v7
	v_lshl_add_u32 v30, v6, 7, s33
	v_lshrrev_b32_e32 v7, 1, v6
	v_lshlrev_b32_e32 v32, 6, v6
	v_max_i32_e32 v6, 0xc0, v116
	v_cmp_ne_u32_e64 s[0:1], 0, v3
	v_and_b32_e32 v0, 15, v116
	v_xor_b32_e32 v7, v7, v116
	v_sub_u32_e32 v6, v6, v116
	v_writelane_b32 v248, s0, 42
	v_lshlrev_b32_e32 v7, 4, v7
	v_add_u32_e32 v6, 63, v6
	v_writelane_b32 v248, s1, 43
	v_cmp_ne_u32_e64 s[0:1], 0, v0
	v_and_b32_e32 v31, 0x70, v7
	v_lshrrev_b32_e32 v7, 6, v6
	v_writelane_b32 v248, s0, 44
	v_add_u32_e32 v7, 1, v7
	v_and_b32_e32 v141, 0x7fffffe, v7
	v_writelane_b32 v248, s1, 45
	v_cmp_lt_u32_e64 s[0:1], 63, v6
	v_and_b32_e32 v8, 7, v116
	v_lshl_add_u32 v111, v0, 2, s33
	v_writelane_b32 v248, s0, 46
	v_lshlrev_b32_e32 v133, 2, v116
	v_lshl_add_u32 v138, v0, 7, s33
	v_writelane_b32 v248, s1, 47
	v_cmp_ne_u32_e64 s[0:1], v7, v141
	v_cmp_gt_u32_e64 s[64:65], 8, v0
	v_xor_b32_e32 v16, v16, v116
	v_writelane_b32 v248, s0, 48
	v_xor_b32_e32 v21, v21, v116
	v_xor_b32_e32 v26, v26, v116
	v_writelane_b32 v248, s1, 49
	v_lshlrev_b32_e32 v0, 7, v8
	v_readlane_b32 s0, v248, 0
	v_ashrrev_i32_e32 v5, 31, v4
	v_lshlrev_b32_e32 v16, 4, v16
	v_add_u32_e32 v145, s0, v11
	v_readlane_b32 s0, v248, 1
	v_lshlrev_b32_e32 v21, 4, v21
	v_lshlrev_b32_e32 v26, 4, v26
	v_lshl_add_u64 v[6:7], s[36:37], 0, v[0:1]
	v_add_u32_e32 v147, s0, v133
	v_readlane_b32 s0, v248, 2
	v_not_b32_e32 v108, v2
	v_lshlrev_b32_e32 v2, 6, v8
	v_add_u32_e32 v137, s33, v9
	v_and_b32_e32 v16, 0x70, v16
	v_and_b32_e32 v21, 0x70, v21
	v_and_b32_e32 v26, 0x70, v26
	v_lshl_add_u64 v[114:115], v[4:5], 1, v[6:7]
	v_ashrrev_i32_e32 v5, 31, v116
	v_mov_b32_e32 v4, v116
	v_add_u32_e32 v148, s0, v9
	v_readlane_b32 s0, v249, 38
	s_mov_b32 s43, s47
	v_lshl_add_u32 v134, v116, 8, s33
	v_cmp_gt_i32_e64 s[46:47], 60, v116
	v_cmp_gt_i32_e64 s[48:49], 56, v116
	v_cmp_gt_i32_e64 s[50:51], 48, v116
	v_cmp_gt_i32_e64 s[52:53], 32, v116
	v_lshl_add_u32 v135, v3, 2, s33
	v_lshl_add_u32 v136, v116, 6, s33
	v_lshlrev_b32_e32 v110, 3, v8
	v_cmp_gt_u32_e64 s[62:63], 32, v116
	v_add_u32_e32 v107, 0x40e0, v137
	v_lshl_add_u32 v142, v141, 6, v116
	v_add_u32_e32 v117, 64, v116
	v_add_u32_e32 v143, 0xffffff00, v133
	v_add_u32_e32 v144, s33, v11
	v_lshl_add_u64 v[118:119], v[4:5], 2, s[22:23]
	v_add_u32_e32 v146, s33, v133
	v_lshlrev_b32_e32 v149, 1, v2
	v_add_u32_e32 v150, v12, v13
	v_add_u32_e32 v151, v10, v14
	v_add_u32_e32 v152, v15, v16
	v_add_u32_e32 v153, v10, v17
	v_add_u32_e32 v154, v18, v13
	v_add_u32_e32 v155, v10, v19
	v_add_u32_e32 v156, v20, v21
	v_add_u32_e32 v157, v10, v22
	v_add_u32_e32 v158, v23, v13
	v_add_u32_e32 v159, v10, v24
	v_add_u32_e32 v160, v25, v26
	v_add_u32_e32 v161, v10, v27
	v_add_u32_e32 v162, v28, v13
	v_add_u32_e32 v163, v10, v29
	v_add_u32_e32 v164, v30, v31
	v_add_u32_e32 v165, v10, v32
	s_mov_b32 s59, s0
	v_readlane_b32 s1, v249, 39
	s_branch .LBB0_571

; #define LAS __attribute__((address_space(3)))
; __global__ void __launch_bounds__(512, 2) mega(Args a) {
;     extern __shared__ __attribute__((aligned(16))) unsigned char lds_raw[];
;     cg::grid_group grid = cg::this_grid();
;     LAS unsigned char* lds = (LAS unsigned char*)lds_raw;
;     const int tid = threadIdx.x, lane = tid & 63, wave = __builtin_amdgcn_readfirstlane(tid >> 6);
;     const int G = gridDim.x, gw = blockIdx.x * 8 + wave, NGW = G * 8;
;     LAS unsigned char* wl = lds + wave * WAVE_LDS;
	.amdhsa_kernel _ZN2mk4megaENS_4ArgsE
		.amdhsa_group_segment_fixed_size 0
		.amdhsa_private_segment_fixed_size 0
		.amdhsa_kernarg_size 392
		.amdhsa_user_sgpr_count 2
		.amdhsa_user_sgpr_dispatch_ptr 0
		.amdhsa_user_sgpr_queue_ptr 0
		.amdhsa_user_sgpr_kernarg_segment_ptr 1
		.amdhsa_user_sgpr_dispatch_id 0
		.amdhsa_user_sgpr_kernarg_preload_length 0
		.amdhsa_user_sgpr_kernarg_preload_offset 0
		.amdhsa_user_sgpr_private_segment_size 0
		.amdhsa_uses_dynamic_stack 0
		.amdhsa_enable_private_segment 0
		.amdhsa_system_sgpr_workgroup_id_x 1
		.amdhsa_system_sgpr_workgroup_id_y 0
		.amdhsa_system_sgpr_workgroup_id_z 0
		.amdhsa_system_sgpr_workgroup_info 0
		.amdhsa_system_vgpr_workitem_id 2
		.amdhsa_next_free_vgpr 252
		.amdhsa_next_free_sgpr 99
		.amdhsa_accum_offset 252
		.amdhsa_reserve_vcc 1
		.amdhsa_float_round_mode_32 0
		.amdhsa_float_round_mode_16_64 0
		.amdhsa_float_denorm_mode_32 3
		.amdhsa_float_denorm_mode_16_64 3
		.amdhsa_dx10_clamp 1
		.amdhsa_ieee_mode 1
		.amdhsa_fp16_overflow 0
		.amdhsa_tg_split 0
		.amdhsa_exception_fp_ieee_invalid_op 0
		.amdhsa_exception_fp_denorm_src 0
		.amdhsa_exception_fp_ieee_div_zero 0
		.amdhsa_exception_fp_ieee_overflow 0
		.amdhsa_exception_fp_ieee_underflow 0
		.amdhsa_exception_fp_ieee_inexact 0
		.amdhsa_exception_int_div_zero 0
	.end_amdhsa_kernel

; __global__ void __launch_bounds__(512, 2) mega(Args a) {
amdhsa.kernels:
  - .agpr_count:     0
    .args:
      - .offset:         0
        .size:           136
        .value_kind:     by_value
      - .offset:         136
        .size:           4
        .value_kind:     hidden_block_count_x
      - .offset:         140
        .size:           4
        .value_kind:     hidden_block_count_y
      - .offset:         144
        .size:           4
        .value_kind:     hidden_block_count_z
      - .offset:         148
        .size:           2
        .value_kind:     hidden_group_size_x
      - .offset:         150
        .size:           2
        .value_kind:     hidden_group_size_y
      - .offset:         152
        .size:           2
        .value_kind:     hidden_group_size_z
      - .offset:         154
        .size:           2
        .value_kind:     hidden_remainder_x
      - .offset:         156
        .size:           2
        .value_kind:     hidden_remainder_y
      - .offset:         158
        .size:           2
        .value_kind:     hidden_remainder_z
      - .offset:         176
        .size:           8
        .value_kind:     hidden_global_offset_x
      - .offset:         184
        .size:           8
        .value_kind:     hidden_global_offset_y
      - .offset:         192
        .size:           8
        .value_kind:     hidden_global_offset_z
      - .offset:         200
        .size:           2
        .value_kind:     hidden_grid_dims
      - .offset:         224
        .size:           8
        .value_kind:     hidden_multigrid_sync_arg
      - .offset:         256
        .size:           4
        .value_kind:     hidden_dynamic_lds_size
    .group_segment_fixed_size: 0
    .kernarg_segment_align: 8
    .kernarg_segment_size: 392
    .language:       OpenCL C
    .language_version:
      - 2
      - 0
    .max_flat_workgroup_size: 512
    .name:           _ZN2mk4megaENS_4ArgsE
    .private_segment_fixed_size: 0
    .sgpr_count:     105
    .sgpr_spill_count: 197
    .symbol:         _ZN2mk4megaENS_4ArgsE.kd
    .uniform_work_group_size: 1
    .uses_dynamic_stack: false
    .vgpr_count:     252
    .vgpr_spill_count: 0
    .wavefront_size: 64
